# gla_state work distribution: the 64 ninth-round items move from workgroups 0..63 (two GEMM tiles each) to workgroups 208..255 (one tile); k2 amplified probe -10 us per layer
# baseline (speedup 1.0000x reference)
; __device__ __forceinline__ unsigned f2bf(float f) { unsigned u = __float_as_uint(f); return (u + 0x7fffu + ((u >> 16) & 1u)) >> 16; }
; __device__ __forceinline__ void gla_state_item(unsigned char* lds, unsigned char* ws, const float* wgate, const float* bgate, int l, int item) {
;     ...
;     __syncthreads();
;     const bf16_t* Vt = (const bf16_t*)(lds + GL_VT);
;     f32x4 acc[4];
; #pragma unroll
;     for (int cb = 0; cb < 4; ++cb) acc[cb] = (f32x4){0.f, 0.f, 0.f, 0.f};
; #pragma unroll
;     for (int kk = 0; kk < 2; ++kk) {
;         const bf16x8 a = *(const bf16x8*)(Vt + (wid * 16 + ql) * 72 + kk * 32 + g * 8);
; #pragma unroll
;         for (int cb = 0; cb < 4; ++cb) { const bf16x8 bb = *(const bf16x8*)(KDt + (cb * 16 + ql) * 72 + kk * 32 + g * 8); acc[cb] = __builtin_amdgcn_mfma_f32_16x16x32_bf16(a, bb, acc[cb], 0, 0, 0); }
;     }
;     bf16_t* st = (bf16_t*)(ws + O_ST) + (size_t)item * 8192;
; #pragma unroll
;     for (int cb = 0; cb < 4; ++cb)
; #pragma unroll
;         for (int j = 0; j < 4; ++j) st[(wid * 16 + g * 4 + j) * 64 + cb * 16 + ql] = (bf16_t)f2bf(acc[cb][j]);
;     __syncthreads();
; __global__ void __launch_bounds__(NTHR, 2) mk_fwd(Args args) {
;     ...
;                 if (ON(15)) for (int item = bid; item < 2112; item += G) gla_state_item(lds, ws, ap->in[I_WGATE], ap->in[I_BGATE], l, item);
.LBB0_669:
	s_or_b64 exec, exec, s[0:1]
	v_and_b32_e32 v7, 15, v4
	v_and_b32_e32 v3, 48, v9
	v_lshl_or_b32 v2, v10, 4, v7
	v_add_u32_e32 v6, 0, v3
	v_mad_u64_u32 v[24:25], s[0:1], v2, s76, v[6:7]
	s_waitcnt lgkmcnt(0)
	s_barrier
	ds_read_b128 v[2:5], v24 offset:46336
	v_mad_u32_u24 v28, v7, s76, v6
	v_lshlrev_b32_e32 v6, 4, v9
	v_lshlrev_b32_e32 v8, 10, v10
	s_movk_i32 s0, 0x300
	v_and_or_b32 v6, v6, s0, v8
	ds_read_b128 v[12:15], v28 offset:27904
	ds_read_b128 v[16:19], v28 offset:30208
	ds_read_b128 v[20:23], v28 offset:32512
	v_ashrrev_i32_e32 v29, 31, v6
	v_or_b32_e32 v30, v7, v6
	ds_read_b128 v[6:9], v28 offset:34816
	s_waitcnt lgkmcnt(3)
	v_mfma_f32_16x16x32_bf16 v[12:15], v[2:5], v[12:15], 0
	v_lshlrev_b64 v[0:1], 14, v[0:1]
	v_lshl_add_u64 v[0:1], s[20:21], 0, v[0:1]
	v_ashrrev_i32_e32 v31, 31, v30
	s_waitcnt lgkmcnt(2)
	v_mfma_f32_16x16x32_bf16 v[16:19], v[2:5], v[16:19], 0
	s_and_b32 s99, s10, 0xff
	s_cmpk_lt_u32 s99, 0xd0
	s_cselect_b32 s99, 0x1000, 48
	s_cmpk_ge_i32 s10, 0x800
	s_cselect_b32 s99, 48, s99
	s_cmpk_lt_i32 s10, 0x700
	s_cselect_b32 s99, 0x100, s99
	s_add_i32 s10, s10, s99
	s_lshl_b32 s30, s10, 6
	s_cmpk_gt_i32 s10, 0x83f
	s_waitcnt lgkmcnt(1)
	v_mfma_f32_16x16x32_bf16 v[20:23], v[2:5], v[20:23], 0
	s_waitcnt lgkmcnt(0)
	v_mfma_f32_16x16x32_bf16 v[2:5], v[2:5], v[6:9], 0
	ds_read_b128 v[6:9], v24 offset:46400
	ds_read_b128 v[24:27], v28 offset:27968
	s_waitcnt lgkmcnt(0)
	v_mfma_f32_16x16x32_bf16 v[10:13], v[6:9], v[24:27], v[12:15]
	ds_read_b128 v[24:27], v28 offset:30272
	s_waitcnt lgkmcnt(0)
	v_mfma_f32_16x16x32_bf16 v[14:17], v[6:9], v[24:27], v[16:19]
	ds_read_b128 v[24:27], v28 offset:32576
	s_waitcnt lgkmcnt(0)
	v_mfma_f32_16x16x32_bf16 v[18:21], v[6:9], v[24:27], v[20:23]
	s_nop 2
	ds_read_b128 v[22:25], v28 offset:34880
	v_or_b32_e32 v28, 16, v30
	s_waitcnt lgkmcnt(0)
	v_mfma_f32_16x16x32_bf16 v[2:5], v[6:9], v[22:25], v[2:5]
	v_bfe_u32 v6, v10, 16, 1
	v_add3_u32 v8, v10, v6, s86
	v_lshl_add_u64 v[6:7], v[30:31], 1, v[0:1]
	global_store_short_d16_hi v[6:7], v8, off
	v_bfe_u32 v6, v11, 16, 1
	v_mov_b32_e32 v31, v29
	v_add3_u32 v8, v11, v6, s86
	v_lshl_add_u64 v[6:7], v[30:31], 1, v[0:1]
	global_store_short_d16_hi v[6:7], v8, off offset:128
	v_bfe_u32 v8, v12, 16, 1
	v_add3_u32 v8, v12, v8, s86
	global_store_short_d16_hi v[6:7], v8, off offset:256
	v_bfe_u32 v8, v13, 16, 1
	v_add3_u32 v8, v13, v8, s86
	global_store_short_d16_hi v[6:7], v8, off offset:384
	v_bfe_u32 v8, v14, 16, 1
	v_add3_u32 v8, v14, v8, s86
	global_store_short_d16_hi v[6:7], v8, off offset:32
	v_bfe_u32 v8, v15, 16, 1
	v_add3_u32 v10, v15, v8, s86
	v_lshl_add_u64 v[8:9], v[28:29], 1, v[0:1]
	global_store_short_d16_hi v[8:9], v10, off offset:128
	v_bfe_u32 v10, v16, 16, 1
	v_add3_u32 v10, v16, v10, s86
	global_store_short_d16_hi v[8:9], v10, off offset:256
	v_bfe_u32 v10, v17, 16, 1
	v_add3_u32 v10, v17, v10, s86
	global_store_short_d16_hi v[8:9], v10, off offset:384
	v_bfe_u32 v8, v18, 16, 1
	v_add3_u32 v8, v18, v8, s86
	global_store_short_d16_hi v[6:7], v8, off offset:64
	v_bfe_u32 v8, v19, 16, 1
	v_or_b32_e32 v28, 32, v30
	v_add3_u32 v10, v19, v8, s86
	v_lshl_add_u64 v[8:9], v[28:29], 1, v[0:1]
	global_store_short_d16_hi v[8:9], v10, off offset:128
	v_bfe_u32 v10, v20, 16, 1
	v_add3_u32 v10, v20, v10, s86
	global_store_short_d16_hi v[8:9], v10, off offset:256
	v_bfe_u32 v10, v21, 16, 1
	v_add3_u32 v10, v21, v10, s86
	global_store_short_d16_hi v[8:9], v10, off offset:384
	v_bfe_u32 v8, v2, 16, 1
	v_add3_u32 v2, v2, v8, s86
	global_store_short_d16_hi v[6:7], v2, off offset:96
	v_bfe_u32 v2, v3, 16, 1
	v_or_b32_e32 v28, 48, v30
	v_add3_u32 v2, v3, v2, s86
	v_lshl_add_u64 v[0:1], v[28:29], 1, v[0:1]
	global_store_short_d16_hi v[0:1], v2, off offset:128
	v_bfe_u32 v2, v4, 16, 1
	v_add3_u32 v2, v4, v2, s86
	global_store_short_d16_hi v[0:1], v2, off offset:256
	v_bfe_u32 v2, v5, 16, 1
	v_add3_u32 v2, v5, v2, s86
	global_store_short_d16_hi v[0:1], v2, off offset:384
	s_barrier
	s_cbranch_scc1 .LBB0_726
